# v29 plus moe_down scatter epilogue de-serialised (16 list-entry loads hoisted, single wait, stores not waited on)
# speedup vs baseline: 1.0151x; 1.0081x over previous
.LBB0_808:
	s_or_b64 exec, exec, s[24:25]
	s_xor_b64 s[24:25], s[26:27], -1
	s_lshl_b32 s26, s38, 7
	v_add_u32_e32 v140, s26, v144
	v_ashrrev_i32_e32 v141, 31, v140
	v_lshl_add_u64 v[140:141], v[130:131], 0, v[140:141]
	v_add_u32_e32 v145, s26, v133
	v_lshl_add_u64 v[140:141], v[140:141], 2, v[138:139]
	s_mov_b32 s38, 0
	v_mov_b32_e32 v146, v158
	s_waitcnt lgkmcnt(0)
	s_barrier
	v_mov_b32_e32 v142, v145
	v_ashrrev_i32_e32 v143, 31, v142
	v_lshl_add_u64 v[148:149], v[142:143], 2, v[134:135]
	global_load_dword v196, v[148:149], off
	global_load_dword v197, v[140:141], off offset:-32
	global_load_dword v198, v[140:141], off
	global_load_dword v199, v[140:141], off offset:32
	v_add_u32_e32 v142, 32, v145
	v_ashrrev_i32_e32 v143, 31, v142
	v_lshl_add_u64 v[148:149], v[142:143], 2, v[134:135]
	global_load_dword v200, v[148:149], off
	global_load_dword v201, v[140:141], off offset:96
	global_load_dword v202, v[140:141], off offset:128
	global_load_dword v203, v[140:141], off offset:160
	v_add_u32_e32 v142, 64, v145
	v_ashrrev_i32_e32 v143, 31, v142
	v_lshl_add_u64 v[148:149], v[142:143], 2, v[134:135]
	global_load_dword v212, v[148:149], off
	global_load_dword v213, v[140:141], off offset:224
	global_load_dword v214, v[140:141], off offset:256
	global_load_dword v215, v[140:141], off offset:288
	v_add_u32_e32 v142, 96, v145
	v_ashrrev_i32_e32 v143, 31, v142
	v_lshl_add_u64 v[148:149], v[142:143], 2, v[134:135]
	global_load_dword v216, v[148:149], off
	global_load_dword v217, v[140:141], off offset:352
	global_load_dword v218, v[140:141], off offset:384
	global_load_dword v219, v[140:141], off offset:416
	ds_read_b128 v[164:167], v146
	ds_read_b128 v[168:171], v146 offset:4224
	ds_read_b128 v[172:175], v146 offset:8448
	ds_read_b128 v[176:179], v146 offset:12672
	s_waitcnt vmcnt(0)
	s_waitcnt lgkmcnt(0)
	v_mov_b32_e32 v142, v145
	v_cmp_lt_i32_e32 vcc, v142, v132
	s_and_saveexec_b64 s[26:27], vcc
	v_cvt_pk_bf16_f32 v180, v164, v165
	v_cvt_pk_bf16_f32 v181, v166, v167
	v_and_b32_e32 v147, 1, v196
	v_ashrrev_i32_e32 v184, 1, v196
	v_cmp_eq_u32_e32 vcc, 1, v147
	v_ashrrev_i32_e32 v185, 31, v184
	s_nop 0
	v_cndmask_b32_e32 v192, 0, v237, vcc
	v_lshl_add_u64 v[184:185], v[192:193], 0, v[184:185]
	v_lshlrev_b64 v[184:185], 11, v[184:185]
	v_lshl_add_u64 v[184:185], v[136:137], 0, v[184:185]
	global_store_dwordx2 v[184:185], v[180:181], off
	s_or_b64 exec, exec, s[26:27]
	v_add_u32_e32 v142, 8, v145
	v_cmp_lt_i32_e32 vcc, v142, v132
	s_and_saveexec_b64 s[26:27], vcc
	v_cvt_pk_bf16_f32 v182, v168, v169
	v_cvt_pk_bf16_f32 v183, v170, v171
	v_and_b32_e32 v147, 1, v197
	v_ashrrev_i32_e32 v186, 1, v197
	v_cmp_eq_u32_e32 vcc, 1, v147
	v_ashrrev_i32_e32 v187, 31, v186
	s_nop 0
	v_cndmask_b32_e32 v192, 0, v237, vcc
	v_lshl_add_u64 v[186:187], v[192:193], 0, v[186:187]
	v_lshlrev_b64 v[186:187], 11, v[186:187]
	v_lshl_add_u64 v[186:187], v[136:137], 0, v[186:187]
	global_store_dwordx2 v[186:187], v[182:183], off
	s_or_b64 exec, exec, s[26:27]
	v_add_u32_e32 v142, 16, v145
	v_cmp_lt_i32_e32 vcc, v142, v132
	s_and_saveexec_b64 s[26:27], vcc
	v_cvt_pk_bf16_f32 v180, v172, v173
	v_cvt_pk_bf16_f32 v181, v174, v175
	v_and_b32_e32 v147, 1, v198
	v_ashrrev_i32_e32 v184, 1, v198
	v_cmp_eq_u32_e32 vcc, 1, v147
	v_ashrrev_i32_e32 v185, 31, v184
	s_nop 0
	v_cndmask_b32_e32 v192, 0, v237, vcc
	v_lshl_add_u64 v[184:185], v[192:193], 0, v[184:185]
	v_lshlrev_b64 v[184:185], 11, v[184:185]
	v_lshl_add_u64 v[184:185], v[136:137], 0, v[184:185]
	global_store_dwordx2 v[184:185], v[180:181], off
	s_or_b64 exec, exec, s[26:27]
	v_add_u32_e32 v142, 24, v145
	v_cmp_lt_i32_e32 vcc, v142, v132
	s_and_saveexec_b64 s[26:27], vcc
	v_cvt_pk_bf16_f32 v182, v176, v177
	v_cvt_pk_bf16_f32 v183, v178, v179
	v_and_b32_e32 v147, 1, v199
	v_ashrrev_i32_e32 v186, 1, v199
	v_cmp_eq_u32_e32 vcc, 1, v147
	v_ashrrev_i32_e32 v187, 31, v186
	s_nop 0
	v_cndmask_b32_e32 v192, 0, v237, vcc
	v_lshl_add_u64 v[186:187], v[192:193], 0, v[186:187]
	v_lshlrev_b64 v[186:187], 11, v[186:187]
	v_lshl_add_u64 v[186:187], v[136:137], 0, v[186:187]
	global_store_dwordx2 v[186:187], v[182:183], off
	s_or_b64 exec, exec, s[26:27]
	ds_read_b128 v[164:167], v146 offset:16896
	ds_read_b128 v[168:171], v146 offset:21120
	ds_read_b128 v[172:175], v146 offset:25344
	ds_read_b128 v[176:179], v146 offset:29568
	s_waitcnt lgkmcnt(0)
	v_add_u32_e32 v142, 32, v145
	v_cmp_lt_i32_e32 vcc, v142, v132
	s_and_saveexec_b64 s[26:27], vcc
	v_cvt_pk_bf16_f32 v180, v164, v165
	v_cvt_pk_bf16_f32 v181, v166, v167
	v_and_b32_e32 v147, 1, v200
	v_ashrrev_i32_e32 v184, 1, v200
	v_cmp_eq_u32_e32 vcc, 1, v147
	v_ashrrev_i32_e32 v185, 31, v184
	s_nop 0
	v_cndmask_b32_e32 v192, 0, v237, vcc
	v_lshl_add_u64 v[184:185], v[192:193], 0, v[184:185]
	v_lshlrev_b64 v[184:185], 11, v[184:185]
	v_lshl_add_u64 v[184:185], v[136:137], 0, v[184:185]
	global_store_dwordx2 v[184:185], v[180:181], off
	s_or_b64 exec, exec, s[26:27]
	v_add_u32_e32 v142, 40, v145
	v_cmp_lt_i32_e32 vcc, v142, v132
	s_and_saveexec_b64 s[26:27], vcc
	v_cvt_pk_bf16_f32 v182, v168, v169
	v_cvt_pk_bf16_f32 v183, v170, v171
	v_and_b32_e32 v147, 1, v201
	v_ashrrev_i32_e32 v186, 1, v201
	v_cmp_eq_u32_e32 vcc, 1, v147
	v_ashrrev_i32_e32 v187, 31, v186
	s_nop 0
	v_cndmask_b32_e32 v192, 0, v237, vcc
	v_lshl_add_u64 v[186:187], v[192:193], 0, v[186:187]
	v_lshlrev_b64 v[186:187], 11, v[186:187]
	v_lshl_add_u64 v[186:187], v[136:137], 0, v[186:187]
	global_store_dwordx2 v[186:187], v[182:183], off
	s_or_b64 exec, exec, s[26:27]
	v_add_u32_e32 v142, 48, v145
	v_cmp_lt_i32_e32 vcc, v142, v132
	s_and_saveexec_b64 s[26:27], vcc
	v_cvt_pk_bf16_f32 v180, v172, v173
	v_cvt_pk_bf16_f32 v181, v174, v175
	v_and_b32_e32 v147, 1, v202
	v_ashrrev_i32_e32 v184, 1, v202
	v_cmp_eq_u32_e32 vcc, 1, v147
	v_ashrrev_i32_e32 v185, 31, v184
	s_nop 0
	v_cndmask_b32_e32 v192, 0, v237, vcc
	v_lshl_add_u64 v[184:185], v[192:193], 0, v[184:185]
	v_lshlrev_b64 v[184:185], 11, v[184:185]
	v_lshl_add_u64 v[184:185], v[136:137], 0, v[184:185]
	global_store_dwordx2 v[184:185], v[180:181], off
	s_or_b64 exec, exec, s[26:27]
	v_add_u32_e32 v142, 56, v145
	v_cmp_lt_i32_e32 vcc, v142, v132
	s_and_saveexec_b64 s[26:27], vcc
	v_cvt_pk_bf16_f32 v182, v176, v177
	v_cvt_pk_bf16_f32 v183, v178, v179
	v_and_b32_e32 v147, 1, v203
	v_ashrrev_i32_e32 v186, 1, v203
	v_cmp_eq_u32_e32 vcc, 1, v147
	v_ashrrev_i32_e32 v187, 31, v186
	s_nop 0
	v_cndmask_b32_e32 v192, 0, v237, vcc
	v_lshl_add_u64 v[186:187], v[192:193], 0, v[186:187]
	v_lshlrev_b64 v[186:187], 11, v[186:187]
	v_lshl_add_u64 v[186:187], v[136:137], 0, v[186:187]
	global_store_dwordx2 v[186:187], v[182:183], off
	s_or_b64 exec, exec, s[26:27]
	ds_read_b128 v[164:167], v146 offset:33792
	ds_read_b128 v[168:171], v146 offset:38016
	ds_read_b128 v[172:175], v146 offset:42240
	ds_read_b128 v[176:179], v146 offset:46464
	s_waitcnt lgkmcnt(0)
	v_add_u32_e32 v142, 64, v145
	v_cmp_lt_i32_e32 vcc, v142, v132
	s_and_saveexec_b64 s[26:27], vcc
	v_cvt_pk_bf16_f32 v180, v164, v165
	v_cvt_pk_bf16_f32 v181, v166, v167
	v_and_b32_e32 v147, 1, v212
	v_ashrrev_i32_e32 v184, 1, v212
	v_cmp_eq_u32_e32 vcc, 1, v147
	v_ashrrev_i32_e32 v185, 31, v184
	s_nop 0
	v_cndmask_b32_e32 v192, 0, v237, vcc
	v_lshl_add_u64 v[184:185], v[192:193], 0, v[184:185]
	v_lshlrev_b64 v[184:185], 11, v[184:185]
	v_lshl_add_u64 v[184:185], v[136:137], 0, v[184:185]
	global_store_dwordx2 v[184:185], v[180:181], off
	s_or_b64 exec, exec, s[26:27]
	v_add_u32_e32 v142, 72, v145
	v_cmp_lt_i32_e32 vcc, v142, v132
	s_and_saveexec_b64 s[26:27], vcc
	v_cvt_pk_bf16_f32 v182, v168, v169
	v_cvt_pk_bf16_f32 v183, v170, v171
	v_and_b32_e32 v147, 1, v213
	v_ashrrev_i32_e32 v186, 1, v213
	v_cmp_eq_u32_e32 vcc, 1, v147
	v_ashrrev_i32_e32 v187, 31, v186
	s_nop 0
	v_cndmask_b32_e32 v192, 0, v237, vcc
	v_lshl_add_u64 v[186:187], v[192:193], 0, v[186:187]
	v_lshlrev_b64 v[186:187], 11, v[186:187]
	v_lshl_add_u64 v[186:187], v[136:137], 0, v[186:187]
	global_store_dwordx2 v[186:187], v[182:183], off
	s_or_b64 exec, exec, s[26:27]
	v_add_u32_e32 v142, 80, v145
	v_cmp_lt_i32_e32 vcc, v142, v132
	s_and_saveexec_b64 s[26:27], vcc
	v_cvt_pk_bf16_f32 v180, v172, v173
	v_cvt_pk_bf16_f32 v181, v174, v175
	v_and_b32_e32 v147, 1, v214
	v_ashrrev_i32_e32 v184, 1, v214
	v_cmp_eq_u32_e32 vcc, 1, v147
	v_ashrrev_i32_e32 v185, 31, v184
	s_nop 0
	v_cndmask_b32_e32 v192, 0, v237, vcc
	v_lshl_add_u64 v[184:185], v[192:193], 0, v[184:185]
	v_lshlrev_b64 v[184:185], 11, v[184:185]
	v_lshl_add_u64 v[184:185], v[136:137], 0, v[184:185]
	global_store_dwordx2 v[184:185], v[180:181], off
	s_or_b64 exec, exec, s[26:27]
	v_add_u32_e32 v142, 88, v145
	v_cmp_lt_i32_e32 vcc, v142, v132
	s_and_saveexec_b64 s[26:27], vcc
	v_cvt_pk_bf16_f32 v182, v176, v177
	v_cvt_pk_bf16_f32 v183, v178, v179
	v_and_b32_e32 v147, 1, v215
	v_ashrrev_i32_e32 v186, 1, v215
	v_cmp_eq_u32_e32 vcc, 1, v147
	v_ashrrev_i32_e32 v187, 31, v186
	s_nop 0
	v_cndmask_b32_e32 v192, 0, v237, vcc
	v_lshl_add_u64 v[186:187], v[192:193], 0, v[186:187]
	v_lshlrev_b64 v[186:187], 11, v[186:187]
	v_lshl_add_u64 v[186:187], v[136:137], 0, v[186:187]
	global_store_dwordx2 v[186:187], v[182:183], off
	s_or_b64 exec, exec, s[26:27]
	ds_read_b128 v[164:167], v146 offset:50688
	ds_read_b128 v[168:171], v146 offset:54912
	ds_read_b128 v[172:175], v146 offset:59136
	ds_read_b128 v[176:179], v146 offset:63360
	s_waitcnt lgkmcnt(0)
	v_add_u32_e32 v142, 96, v145
	v_cmp_lt_i32_e32 vcc, v142, v132
	s_and_saveexec_b64 s[26:27], vcc
	v_cvt_pk_bf16_f32 v180, v164, v165
	v_cvt_pk_bf16_f32 v181, v166, v167
	v_and_b32_e32 v147, 1, v216
	v_ashrrev_i32_e32 v184, 1, v216
	v_cmp_eq_u32_e32 vcc, 1, v147
	v_ashrrev_i32_e32 v185, 31, v184
	s_nop 0
	v_cndmask_b32_e32 v192, 0, v237, vcc
	v_lshl_add_u64 v[184:185], v[192:193], 0, v[184:185]
	v_lshlrev_b64 v[184:185], 11, v[184:185]
	v_lshl_add_u64 v[184:185], v[136:137], 0, v[184:185]
	global_store_dwordx2 v[184:185], v[180:181], off
	s_or_b64 exec, exec, s[26:27]
	v_add_u32_e32 v142, 104, v145
	v_cmp_lt_i32_e32 vcc, v142, v132
	s_and_saveexec_b64 s[26:27], vcc
	v_cvt_pk_bf16_f32 v182, v168, v169
	v_cvt_pk_bf16_f32 v183, v170, v171
	v_and_b32_e32 v147, 1, v217
	v_ashrrev_i32_e32 v186, 1, v217
	v_cmp_eq_u32_e32 vcc, 1, v147
	v_ashrrev_i32_e32 v187, 31, v186
	s_nop 0
	v_cndmask_b32_e32 v192, 0, v237, vcc
	v_lshl_add_u64 v[186:187], v[192:193], 0, v[186:187]
	v_lshlrev_b64 v[186:187], 11, v[186:187]
	v_lshl_add_u64 v[186:187], v[136:137], 0, v[186:187]
	global_store_dwordx2 v[186:187], v[182:183], off
	s_or_b64 exec, exec, s[26:27]
	v_add_u32_e32 v142, 112, v145
	v_cmp_lt_i32_e32 vcc, v142, v132
	s_and_saveexec_b64 s[26:27], vcc
	v_cvt_pk_bf16_f32 v180, v172, v173
	v_cvt_pk_bf16_f32 v181, v174, v175
	v_and_b32_e32 v147, 1, v218
	v_ashrrev_i32_e32 v184, 1, v218
	v_cmp_eq_u32_e32 vcc, 1, v147
	v_ashrrev_i32_e32 v185, 31, v184
	s_nop 0
	v_cndmask_b32_e32 v192, 0, v237, vcc
	v_lshl_add_u64 v[184:185], v[192:193], 0, v[184:185]
	v_lshlrev_b64 v[184:185], 11, v[184:185]
	v_lshl_add_u64 v[184:185], v[136:137], 0, v[184:185]
	global_store_dwordx2 v[184:185], v[180:181], off
	s_or_b64 exec, exec, s[26:27]
	v_add_u32_e32 v142, 120, v145
	v_cmp_lt_i32_e32 vcc, v142, v132
	s_and_saveexec_b64 s[26:27], vcc
	v_cvt_pk_bf16_f32 v182, v176, v177
	v_cvt_pk_bf16_f32 v183, v178, v179
	v_and_b32_e32 v147, 1, v219
	v_ashrrev_i32_e32 v186, 1, v219
	v_cmp_eq_u32_e32 vcc, 1, v147
	v_ashrrev_i32_e32 v187, 31, v186
	s_nop 0
	v_cndmask_b32_e32 v192, 0, v237, vcc
	v_lshl_add_u64 v[186:187], v[192:193], 0, v[186:187]
	v_lshlrev_b64 v[186:187], 11, v[186:187]
	v_lshl_add_u64 v[186:187], v[136:137], 0, v[186:187]
	global_store_dwordx2 v[186:187], v[182:183], off
	s_or_b64 exec, exec, s[26:27]
	s_branch .LBB0_805
